# MLA inner loop unrolled by two trips: LDS ring slots become immediates (no per-tile address VALU, tile-index SALU only on the DMA waves, last-tile mask test only in the second copy)
# speedup vs baseline: 1.1145x; 1.0155x over previous
; DEVINL i32x8 mk6(int a, int b, int c, int d, int e, int f) { i32x8 r = __builtin_nondeterministic_value(r); r[0] = a; r[1] = b; r[2] = c; r[3] = d; r[4] = e; r[5] = f; return r; }
; #define MFMA6(A, B, C) __builtin_amdgcn_mfma_scale_f32_32x32x64_f8f6f4(A, B, C, 2, 2, 0, 0x7f7f7f7f, 0, 0x7f7f7f7f)
; #define ISSUE_K(j) do { const int _t = (j) < NT ? (j) : NT - 1; char* _d = K_lds + ((j) & 3) * SHM_K8; if (wid < 6) GLDS(K8 + (size_t)_t * 6144 + t16u, _d + tid16); \
;     if (wid < 3) GLDS(Kp8 + (size_t)_t * 3072 + t16u, _d + 6144 + tid16); } while (0)
; #define ISSUE_V(j) do { const int _t = (j) < NT ? (j) : NT - 1; GLDS(V8 + (size_t)_t * 8192 + t16u, V_lds + ((j) & 3) * SHM_V8 + tid16); } while (0)
; #define TILE_SYNC() do { asm volatile("s_waitcnt vmcnt(0)" ::: "memory"); __syncthreads(); } while (0)
; template <bool FUSE>
; DEVINL void qkt(f32x16& p0, f32x16& p1, const char* Ks, const i32x8* q8, int r32, int hi, f32x16& e1) {
;   p0 = f32x16{}; p1 = f32x16{};
;   const char* ka = Ks + hi * 1024 + r32 * 16; const char* kb = Ks + 4096 + hi * 512 + r32 * 8;
;   const char* ra = Ks + 6144 + hi * 1024 + r32 * 16; const char* rb = Ks + 6144 + 2048 + hi * 512 + r32 * 8;
;   u32x4 fa[3][2]; u32x2 fb[3][2];
;     ...
;   QK_LD(0, 0);
; #pragma unroll
;   for (int t = 0; t < 3; ++t) {
;     if (t + 1 < 3) QK_LD(t + 1, (t + 1) % 3);
;     const i32x8 a0 = mk6((int)fa[t][0][0], (int)fa[t][0][1], (int)fa[t][0][2], (int)fa[t][0][3], (int)fb[t][0][0], (int)fb[t][0][1]);
;     const i32x8 a1 = mk6((int)fa[t][1][0], (int)fa[t][1][1], (int)fa[t][1][2], (int)fa[t][1][3], (int)fb[t][1][0], (int)fb[t][1][1]);
;     p0 = MFMA6(a0, q8[t], p0);
; DEVINL void mla_block(const Params& p, const bf16_t* __restrict__ Qn, const bf16_t* __restrict__ Qr, const char* __restrict__ K8, const char* __restrict__ Kp8,
;                       const char* __restrict__ V8, const bf16_t* __restrict__ Gb, bf16_t* __restrict__ Yb, char* lds, int pos0) {
;     ...
;   ISSUE_K(0); ISSUE_K(1); ISSUE_K(2); ISSUE_V(0); ISSUE_V(1); TILE_SYNC();
;   qkt<false>(pA0, pA1, KS(0), q8, r32, hi, pA1); partialSM(pA0, pA1, m_reg, mnA, alA, 64, hi);
.LBB0_559:
	s_or_b64 exec, exec, s[8:9]
	s_mul_i32 s8, s75, 0x208000
	s_add_u32 s14, s58, s8
	v_add_u32_e32 v0, 0x9000, v172
	s_addc_u32 s15, s59, 0
	v_readfirstlane_b32 s9, v0
	v_add_u32_e32 v2, 0xb000, v172
	v_lshl_add_u64 v[140:141], s[14:15], 0, v[138:139]
	s_mov_b32 m0, s9
	v_readfirstlane_b32 s9, v2
	global_load_lds_dwordx4 v[140:141], off
	v_lshl_add_u64 v[0:1], v[140:141], 0, s[48:49]
	s_mov_b32 m0, s9
	v_lshlrev_b32_e32 v170, 9, v48
	global_load_lds_dwordx4 v[0:1], off
	v_and_b32_e32 v0, 0x3fffffc0, v166
	v_lshl_add_u32 v171, v0, 2, s68
	v_add_u32_e32 v0, 0, v170
	v_lshlrev_b32_e32 v176, 3, v167
	v_lshlrev_b32_e32 v175, 4, v167
	v_add_u32_e32 v49, v0, v176
	v_add3_u32 v173, v0, v170, v175
	v_add_u32_e32 v0, 0x1000, v49
	s_waitcnt vmcnt(0)
	s_waitcnt vmcnt(0) lgkmcnt(0)
	s_barrier
	ds_read2_b64 v[4:7], v0 offset1:32
	ds_read_b128 v[50:53], v173 offset:2048
	ds_read_b128 v[56:59], v173 offset:2560
	ds_read2_b64 v[60:63], v0 offset0:128 offset1:160
	ds_read_b128 v[16:19], v173 offset:512
	ds_read_b128 v[0:3], v173
	s_waitcnt lgkmcnt(5)
	v_mov_b32_e32 v20, v6
	v_mov_b32_e32 v21, v7
	s_waitcnt lgkmcnt(0)
	v_mfma_scale_f32_32x32x64_f8f6f4 v[32:47], v[0:5], v[120:125], 0, v162, v162 op_sel_hi:[0,0,0] cbsz:2 blgp:2
	s_mov_b32 s12, s13
	s_mov_b32 s14, s13
	s_mov_b32 s15, s13
	s_mov_b32 s16, s13
	s_mov_b32 s17, s13
	s_mov_b32 s18, s13
	s_mov_b32 s19, s13
	v_mfma_scale_f32_32x32x64_f8f6f4 v[16:31], v[16:21], v[120:125], 0, v162, v162 op_sel_hi:[0,0,0] cbsz:2 blgp:2
	s_mov_b32 s20, s13
	s_mov_b32 s21, s13
	s_mov_b32 s22, s13
	s_mov_b32 s23, s13
	s_mov_b32 s24, s13
	s_mov_b32 s25, s13
	s_mov_b32 s26, s13
	s_mov_b32 s27, s13
	v_mov_b64_e32 v[0:1], s[12:13]
	v_and_b32_e32 v169, 63, v166
	v_lshlrev_b32_e32 v174, 10, v48
	s_mov_b32 s53, 4
	v_mov_b64_e32 v[2:3], s[14:15]
	v_mov_b64_e32 v[4:5], s[16:17]
	v_mov_b64_e32 v[6:7], s[18:19]
	v_mov_b64_e32 v[8:9], s[20:21]
	v_mov_b64_e32 v[10:11], s[22:23]
	v_mov_b64_e32 v[12:13], s[24:25]
	v_mov_b64_e32 v[14:15], s[26:27]
	v_mov_b32_e32 v54, v60
	v_mov_b32_e32 v55, v61
	v_mov_b32_e32 v60, v62
	v_mov_b32_e32 v61, v63
	v_add_u32_e32 v49, 0x2000, v49
	v_mfma_scale_f32_32x32x64_f8f6f4 v[32:47], v[50:55], v[126:131], v[32:47], v162, v162 op_sel_hi:[0,0,0] cbsz:2 blgp:2
	ds_read_b128 v[50:53], v173 offset:6144
	ds_read_b128 v[62:65], v173 offset:6656
	ds_read2_b64 v[66:69], v49 offset1:32
	v_mfma_scale_f32_32x32x64_f8f6f4 v[16:31], v[56:61], v[126:131], v[16:31], v162, v162 op_sel_hi:[0,0,0] cbsz:2 blgp:2
	s_waitcnt lgkmcnt(0)
; #define SBAR() __builtin_amdgcn_sched_barrier(0)
; #define ISSUE_K(j) do { const int _t = (j) < NT ? (j) : NT - 1; char* _d = K_lds + ((j) & 3) * SHM_K8; if (wid < 6) GLDS(K8 + (size_t)_t * 6144 + t16u, _d + tid16); \
;     if (wid < 3) GLDS(Kp8 + (size_t)_t * 3072 + t16u, _d + 6144 + tid16); } while (0)
; #define ISSUE_V(j) do { const int _t = (j) < NT ? (j) : NT - 1; GLDS(V8 + (size_t)_t * 8192 + t16u, V_lds + ((j) & 3) * SHM_V8 + tid16); } while (0)
; DEVINL void mla_block(const Params& p, const bf16_t* __restrict__ Qn, const bf16_t* __restrict__ Qr, const char* __restrict__ K8, const char* __restrict__ Kp8,
;                       const char* __restrict__ V8, const bf16_t* __restrict__ Gb, bf16_t* __restrict__ Yb, char* lds, int pos0) {
;     ...
;     ISSUE_K(j + 2); ISSUE_K(j + 3); ISSUE_V(j + 1); ISSUE_V(j + 2); SBAR();
	v_mov_b32_e32 v54, v66
	v_mov_b32_e32 v55, v67
	v_mov_b32_e32 v66, v68
	v_mov_b32_e32 v67, v69
	v_mfma_scale_f32_32x32x64_f8f6f4 v[32:47], v[50:55], v[132:137], v[32:47], v162, v162 op_sel_hi:[0,0,0] cbsz:2 blgp:2
	s_nop 0
	v_mfma_scale_f32_32x32x64_f8f6f4 v[16:31], v[62:67], v[132:137], v[16:31], v162, v162 op_sel_hi:[0,0,0] cbsz:2 blgp:2
	s_nop 9
	v_max_f32_e32 v49, v33, v33
	v_max_f32_e32 v50, v32, v32
	v_max_f32_e32 v49, v50, v49
	v_max3_f32 v49, v49, v34, v35
	v_max3_f32 v49, v49, v36, v37
	v_max3_f32 v49, v49, v38, v39
	v_max3_f32 v49, v49, v40, v41
	v_max3_f32 v49, v49, v42, v43
	v_max3_f32 v49, v49, v44, v45
	v_max3_f32 v49, v49, v46, v47
	v_max3_f32 v49, v49, v16, v17
	v_max3_f32 v49, v49, v18, v19
	v_max3_f32 v49, v49, v20, v21
	v_max3_f32 v49, v49, v22, v23
	v_max3_f32 v49, v49, v24, v25
	v_max3_f32 v49, v49, v26, v27
	v_max3_f32 v49, v49, v28, v29
	v_max3_f32 v49, v49, v30, v31
	v_mov_b32_e32 v50, v49
	s_nop 1
	v_permlane32_swap_b32_e32 v49, v50
	v_max_f32_e32 v50, v50, v50
	v_max_f32_e32 v49, v49, v49
	v_max_f32_e32 v49, v49, v50
	v_add_f32_e32 v50, 0x7149f2ca, v49
	v_max_f32_e32 v49, 0xf149f2ca, v49
	v_sub_f32_e32 v51, 0xf149f2ca, v49
	v_mul_f32_e32 v51, 0x3dd53b94, v51
	v_cmp_ge_f32_e32 vcc, s69, v50
	v_exp_f32_e32 v51, v51
	s_cmp_eq_u64 vcc, exec
	s_cselect_b64 vcc, -1, 0
	v_cndmask_b32_e32 v181, v49, v163, vcc
	v_fmamk_f32 v50, v181, 0xbdd53b94, v164
	v_pk_fma_f32 v[32:33], v[32:33], s[50:51], v[50:51] op_sel_hi:[1,0,0]
	v_pk_fma_f32 v[34:35], v[34:35], s[50:51], v[50:51] op_sel_hi:[1,0,0]
	v_pk_fma_f32 v[36:37], v[36:37], s[50:51], v[50:51] op_sel_hi:[1,0,0]
	v_pk_fma_f32 v[38:39], v[38:39], s[50:51], v[50:51] op_sel_hi:[1,0,0]
	v_pk_fma_f32 v[40:41], v[40:41], s[50:51], v[50:51] op_sel_hi:[1,0,0]
	v_pk_fma_f32 v[42:43], v[42:43], s[50:51], v[50:51] op_sel_hi:[1,0,0]
	v_pk_fma_f32 v[44:45], v[44:45], s[50:51], v[50:51] op_sel_hi:[1,0,0]
	v_pk_fma_f32 v[46:47], v[46:47], s[50:51], v[50:51] op_sel_hi:[1,0,0]
	v_exp_f32_e32 v65, v32
	v_exp_f32_e32 v197, v33
	v_exp_f32_e32 v187, v34
	v_exp_f32_e32 v189, v35
	v_exp_f32_e32 v195, v36
	v_exp_f32_e32 v196, v37
	v_exp_f32_e32 v191, v38
	v_exp_f32_e32 v192, v39
	v_exp_f32_e32 v193, v40
	v_exp_f32_e32 v194, v41
	v_exp_f32_e32 v183, v42
	v_exp_f32_e32 v184, v43
	v_exp_f32_e32 v188, v44
	v_exp_f32_e32 v190, v45
	v_exp_f32_e32 v185, v46
	v_exp_f32_e32 v186, v47
	s_add_u32 s8, s30, s8
	v_cndmask_b32_e64 v179, v51, 1.0, vcc
	v_pk_fma_f32 v[148:149], v[30:31], s[50:51], v[50:51] op_sel_hi:[1,0,0]
	v_pk_fma_f32 v[150:151], v[28:29], s[50:51], v[50:51] op_sel_hi:[1,0,0]
	v_pk_fma_f32 v[152:153], v[26:27], s[50:51], v[50:51] op_sel_hi:[1,0,0]
	v_pk_fma_f32 v[154:155], v[24:25], s[50:51], v[50:51] op_sel_hi:[1,0,0]
	v_pk_fma_f32 v[156:157], v[22:23], s[50:51], v[50:51] op_sel_hi:[1,0,0]
	v_pk_fma_f32 v[82:83], v[20:21], s[50:51], v[50:51] op_sel_hi:[1,0,0]
	v_pk_fma_f32 v[158:159], v[18:19], s[50:51], v[50:51] op_sel_hi:[1,0,0]
	v_pk_fma_f32 v[160:161], v[16:17], s[50:51], v[50:51] op_sel_hi:[1,0,0]
	v_lshlrev_b32_e32 v177, 4, v48
	s_addc_u32 s9, s31, 0
	v_mov_b64_e32 v[62:63], v[14:15]
	v_mov_b64_e32 v[30:31], v[14:15]
	v_mov_b64_e32 v[46:47], v[14:15]
	v_lshl_add_u64 v[142:143], s[6:7], 0, v[138:139]
	v_lshl_add_u64 v[144:145], s[34:35], 0, v[138:139]
	v_cmp_gt_u32_e64 s[6:7], 32, v169
	v_lshl_add_u32 v178, v167, 2, v171
	v_lshl_add_u64 v[146:147], s[8:9], 0, v[138:139]
	v_mov_b32_e32 v180, 0
	s_mov_b64 s[14:15], 0x89dc400
	v_mov_b64_e32 v[60:61], v[12:13]
	v_mov_b64_e32 v[58:59], v[10:11]
	v_mov_b64_e32 v[56:57], v[8:9]
	v_mov_b64_e32 v[54:55], v[6:7]
	v_mov_b64_e32 v[52:53], v[4:5]
	v_mov_b64_e32 v[50:51], v[2:3]
	v_mov_b64_e32 v[48:49], v[0:1]
	v_mov_b64_e32 v[28:29], v[12:13]
	v_mov_b64_e32 v[26:27], v[10:11]
	v_mov_b64_e32 v[24:25], v[8:9]
	v_mov_b64_e32 v[22:23], v[6:7]
	v_mov_b64_e32 v[20:21], v[4:5]
	v_mov_b64_e32 v[18:19], v[2:3]
	v_mov_b64_e32 v[16:17], v[0:1]
	v_mov_b64_e32 v[44:45], v[12:13]
	v_mov_b64_e32 v[42:43], v[10:11]
	v_mov_b64_e32 v[40:41], v[8:9]
	v_mov_b64_e32 v[38:39], v[6:7]
	v_mov_b64_e32 v[36:37], v[4:5]
	v_mov_b64_e32 v[34:35], v[2:3]
	v_mov_b64_e32 v[32:33], v[0:1]
	v_mov_b32_e32 v232, v112
	v_mov_b32_e32 v233, v112
	v_mov_b32_e32 v234, v112
	v_mov_b32_e32 v235, v112
	v_mov_b32_e32 v236, v112
	v_mov_b32_e32 v237, v112
	v_mov_b32_e32 v238, v112
	v_mov_b32_e32 v239, v112
	v_add_u32_e32 v176, v170, v176
	v_add_u32_e32 v176, 0x1000, v176
	v_add_u32_e32 v174, 0x2400, v173
	v_add_u32_e32 v175, 0x2400, v176
	ds_read_b128 v[204:207], v174
	ds_read_b64 v[208:209], v175
	ds_read_b128 v[216:219], v174 offset:512
	ds_read_b64 v[220:221], v175 offset:256
	s_lshl_b32 s78, s3, 4
	s_add_i32 s79, s78, 0x9000
	s_mul_i32 s80, s75, 0x186000
	s_add_u32 s80, s56, s80
	s_addc_u32 s81, s57, 0
	s_mov_b64 s[82:83], s[34:35]
	s_mul_i32 s84, s75, 0x208000
	s_add_u32 s84, s58, s84
	s_addc_u32 s85, s59, 0
	v_lshlrev_b32_e32 v231, 4, v169
	v_mov_b32_e32 v227, v181
	v_fmamk_f32 v230, v181, 0xbdd53b94, v164
	v_add_u32_e32 v140, 0x8000, v173
	s_cmp_ge_u32 s3, 0x100
	s_cbranch_scc1 .Lprio_skip
	s_setprio 2
.Lprio_skip:
.LBB0_560:
	s_cmp_lt_u32 s3, 0x100
	s_cbranch_scc1 .Ldma_done
	s_add_i32 s8, s53, -1
	s_cmpk_lg_i32 s53, 0x102
	s_cselect_b32 s17, s8, 0x100
	s_and_b32 s16, s8, 3
	s_add_i32 s18, s53, -3
	s_cmpk_lt_u32 s18, 0xfe
	s_cselect_b32 s86, s53, 0x100
	s_and_b32 s87, s53, 3
	s_add_i32 s19, s53, -2
	s_and_b32 s20, s19, 3
	s_cmp_lt_u32 s3, 0x180
	s_cbranch_scc1 .Ldma_v
	s_cmp_ge_u32 s3, 0x1c0
	s_cselect_b32 s88, s86, s17
	s_cselect_b32 s89, s87, s16
	s_mul_i32 s89, s89, 0x2400
	s_mul_i32 s92, s88, 0x1800
	s_add_u32 s90, s80, s92
	s_addc_u32 s91, s81, 0
	s_mov_b32 m0, s89
	s_mul_i32 s92, s88, 0xc00
	global_load_lds_dwordx4 v231, s[90:91]
	global_load_lds_dwordx4 v231, s[90:91] offset:1024
	global_load_lds_dwordx4 v231, s[90:91] offset:2048
	global_load_lds_dwordx4 v231, s[90:91] offset:3072
	s_add_u32 s90, s90, 0x1000
	s_addc_u32 s91, s91, 0
	s_add_i32 s88, s89, 0x1000
	s_mov_b32 m0, s88
	s_add_i32 s89, s89, 0x1800
	global_load_lds_dwordx4 v231, s[90:91]
	global_load_lds_dwordx4 v231, s[90:91] offset:1024
	s_add_u32 s90, s82, s92
	s_addc_u32 s91, s83, 0
	s_mov_b32 m0, s89
	s_nop 0
	global_load_lds_dwordx4 v231, s[90:91]
	global_load_lds_dwordx4 v231, s[90:91] offset:1024
	global_load_lds_dwordx4 v231, s[90:91] offset:2048
	s_branch .Ldma_done

; #define SBAR() __builtin_amdgcn_sched_barrier(0)
; #define RESC(a) do { if (__any((a) < 1.f)) { if (hi == 0) al_l[r32] = (a); asm volatile("s_waitcnt lgkmcnt(0)" ::: "memory"); \
;     for (int d = 0; d < 4; ++d) for (int r = 0; r < 16; ++r) o[d][r] *= al_l[crow(r, hi)]; } } while (0)
; #define LUPD(al) do { l_reg = l_reg * (al) + lsum[0]; } while (0)
; DEVINL void pv_load(VFrag& f, const char* Vs, int r32, int hi) {
;   const char* vb = Vs + hi * 1024 + r32 * 16;
; #pragma unroll
;   for (int db = 0; db < 4; ++db) { f.v[db][0] = *reinterpret_cast<const u32x4*>(vb + db * 2048); f.v[db][1] = *reinterpret_cast<const u32x4*>(vb + db * 2048 + 512); }
; }
; DEVINL void mla_block(const Params& p, const bf16_t* __restrict__ Qn, const bf16_t* __restrict__ Qr, const char* __restrict__ K8, const char* __restrict__ Kp8,
;                       const char* __restrict__ V8, const bf16_t* __restrict__ Gb, bf16_t* __restrict__ Yb, char* lds, int pos0) {
;     ...
;     qkt<true>(pB0, pB1, KS(j), q8, r32, hi, pA1);
;     pv_load(vf, VS(j - 1), r32, hi); SBAR();
;     finishSM<true>(pA0, pA1, alA, l_reg, pa); SBAR();
;     pv_psm(o, vf, pa, lsum, ones8, pB0, pB1, m_reg, mnB, alB, 64, hi);
;     LUPD(alA); RESC(alB); SBAR();
;     qkt<true>(pA0, pA1, KS(j + 1), q8, r32, hi, pB1);
.Ldma_done:
	ds_read_b128 v[114:117], v173 offset:11264
	ds_read_b128 v[198:201], v173 offset:11776
	ds_read_b64 v[118:119], v176 offset:10240
	ds_read_b64 v[202:203], v176 offset:10496
	v_exp_f32_e32 v182, v82
	s_waitcnt lgkmcnt(4)
	v_exp_f32_e32 v214, v83
	v_mfma_scale_f32_32x32x64_f8f6f4 v[96:111], v[204:209], v[120:125], 0, v162, v162 op_sel_hi:[0,0,0] cbsz:2 blgp:2
	v_exp_f32_e32 v160, v160
	v_exp_f32_e32 v161, v161
	v_exp_f32_e32 v158, v158
	v_exp_f32_e32 v159, v159
	v_mfma_scale_f32_32x32x64_f8f6f4 v[80:95], v[216:221], v[120:125], 0, v162, v162 op_sel_hi:[0,0,0] cbsz:2 blgp:2
	ds_read_b128 v[66:69], v173 offset:15360
	ds_read_b128 v[72:75], v173 offset:15872
	ds_read_b64 v[70:71], v176 offset:13312
	ds_read_b64 v[76:77], v176 offset:13568
	s_waitcnt lgkmcnt(4)
	v_mfma_scale_f32_32x32x64_f8f6f4 v[96:111], v[114:119], v[126:131], v[96:111], v162, v162 op_sel_hi:[0,0,0] cbsz:2 blgp:2
	v_exp_f32_e32 v113, v156
	v_exp_f32_e32 v114, v157
	v_exp_f32_e32 v115, v154
	v_exp_f32_e32 v116, v155
	v_exp_f32_e32 v117, v152
	v_mfma_scale_f32_32x32x64_f8f6f4 v[80:95], v[198:203], v[126:131], v[80:95], v162, v162 op_sel_hi:[0,0,0] cbsz:2 blgp:2
	v_exp_f32_e32 v118, v153
	s_waitcnt lgkmcnt(0)
	v_exp_f32_e32 v119, v150
	v_mfma_scale_f32_32x32x64_f8f6f4 v[96:111], v[66:71], v[132:137], v[96:111], v162, v162 op_sel_hi:[0,0,0] cbsz:2 blgp:2
	v_exp_f32_e32 v156, v151
	v_exp_f32_e32 v157, v148
	v_exp_f32_e32 v215, v149
	v_mfma_scale_f32_32x32x64_f8f6f4 v[80:95], v[72:77], v[132:137], v[80:95], v162, v162 op_sel_hi:[0,0,0] cbsz:2 blgp:2
	ds_read_b128 v[72:75], v140 offset:4096
	ds_read_b128 v[76:79], v140 offset:4608
	ds_read_b128 v[148:151], v140 offset:6144
	ds_read_b128 v[152:155], v140 offset:6656
	ds_read_b128 v[198:201], v140 offset:8192
	ds_read_b128 v[202:205], v140 offset:8704
	ds_read_b128 v[206:209], v140 offset:10240
	ds_read_b128 v[210:213], v140 offset:10752
	v_cvt_pk_fp8_f32 v64, v65, v197
	v_cvt_pk_fp8_f32 v68, v160, v161
	v_cvt_pk_fp8_f32 v65, v195, v196
	v_cvt_pk_fp8_f32 v69, v182, v214
	v_cvt_pk_fp8_f32 v66, v193, v194
	v_cvt_pk_fp8_f32 v70, v115, v116
	v_cvt_pk_fp8_f32 v67, v188, v190
	v_cvt_pk_fp8_f32 v71, v119, v156
	v_cvt_pk_fp8_f32 v64, v187, v189 op_sel:[0,0,1]
	v_cvt_pk_fp8_f32 v68, v158, v159 op_sel:[0,0,1]
	v_cvt_pk_fp8_f32 v65, v191, v192 op_sel:[0,0,1]
	v_cvt_pk_fp8_f32 v69, v113, v114 op_sel:[0,0,1]
	v_cvt_pk_fp8_f32 v66, v183, v184 op_sel:[0,0,1]
	v_cvt_pk_fp8_f32 v70, v117, v118 op_sel:[0,0,1]
	v_cvt_pk_fp8_f32 v67, v185, v186 op_sel:[0,0,1]
	v_cvt_pk_fp8_f32 v71, v157, v215 op_sel:[0,0,1]
	s_waitcnt lgkmcnt(0)
	s_nop 0
	v_mfma_scale_f32_32x32x64_f8f6f4 v[0:15], v[64:71], v[72:79], v[0:15], v162, v162 op_sel_hi:[0,0,0]
	v_max_f32_e32 v113, v96, v97
	v_max3_f32 v113, v113, v98, v99
	v_max3_f32 v113, v113, v100, v101
	v_max3_f32 v113, v113, v102, v103
	v_max3_f32 v113, v113, v104, v105
	v_max3_f32 v113, v113, v106, v107
	v_max3_f32 v113, v113, v108, v109
	v_max3_f32 v113, v113, v110, v111
	v_mfma_scale_f32_32x32x64_f8f6f4 v[48:63], v[64:71], v[148:155], v[48:63], v162, v162 op_sel_hi:[0,0,0]
	v_max3_f32 v72, v113, v80, v81
	v_max3_f32 v72, v72, v82, v83
	v_max3_f32 v72, v72, v84, v85
	v_max3_f32 v72, v72, v86, v87
	v_max3_f32 v72, v72, v88, v89
	v_max3_f32 v72, v72, v90, v91
	v_max3_f32 v72, v72, v92, v93
	v_max3_f32 v72, v72, v94, v95
	v_mov_b32_e32 v73, v72
	s_nop 1
	v_permlane32_swap_b32_e32 v72, v73
	v_max_f32_e32 v72, v72, v73
	v_mfma_scale_f32_32x32x64_f8f6f4 v[16:31], v[64:71], v[198:205], v[16:31], v162, v162 op_sel_hi:[0,0,0]
	v_sub_f32_e32 v73, v72, v227
	v_cmp_ge_f32_e32 vcc, s69, v73
	s_cmp_eq_u64 vcc, exec
	s_cselect_b64 s[8:9], -1, 0
	v_mov_b32_e32 v182, 1.0
	v_mfma_scale_f32_32x32x64_f8f6f4 v[32:47], v[64:71], v[206:213], v[32:47], v162, v162 op_sel_hi:[0,0,0]
	v_mfma_scale_f32_32x32x64_f8f6f4 v[240:255], v[232:239], v[64:71], 0, v162, v162 op_sel_hi:[0,0,0]
	ds_read_b128 v[200:203], v173 offset:18432
	ds_read_b64 v[204:205], v176 offset:18432
	ds_read_b128 v[206:209], v173 offset:18944
	ds_read_b64 v[210:211], v176 offset:18688
	s_and_b64 vcc, exec, s[8:9]
	s_cbranch_vccnz .LBB0_572
	v_max_f32_e32 v148, v227, v72
	v_sub_f32_e32 v72, v227, v148
	v_mul_f32_e32 v72, 0x3dd53b94, v72
	v_exp_f32_e32 v182, v72
	v_mov_b32_e32 v227, v148
	v_fmamk_f32 v230, v148, 0xbdd53b94, v164
	s_and_saveexec_b64 s[16:17], s[6:7]
	ds_write_b32 v178, v182 offset:128
	s_or_b64 exec, exec, s[16:17]
	s_waitcnt lgkmcnt(0)
	v_add_u32_e32 v113, v171, v177
	ds_read_b128 v[72:75], v113 offset:224
	ds_read_b128 v[76:79], v113 offset:192
	ds_read_b128 v[114:117], v113 offset:160
	ds_read_b128 v[150:153], v113 offset:128
	s_waitcnt lgkmcnt(0)
	v_pk_mul_f32 v[12:13], v[12:13], v[72:73]
	v_pk_mul_f32 v[8:9], v[8:9], v[76:77]
	v_pk_mul_f32 v[4:5], v[4:5], v[114:115]
	v_pk_mul_f32 v[14:15], v[14:15], v[74:75]
	v_pk_mul_f32 v[10:11], v[10:11], v[78:79]
	v_pk_mul_f32 v[6:7], v[6:7], v[116:117]
	v_pk_mul_f32 v[2:3], v[2:3], v[152:153]
	v_pk_mul_f32 v[0:1], v[0:1], v[150:151]
	v_pk_mul_f32 v[60:61], v[60:61], v[72:73]
	v_pk_mul_f32 v[56:57], v[56:57], v[76:77]
	v_pk_mul_f32 v[52:53], v[52:53], v[114:115]
	v_pk_mul_f32 v[62:63], v[62:63], v[74:75]
	v_pk_mul_f32 v[58:59], v[58:59], v[78:79]
	v_pk_mul_f32 v[54:55], v[54:55], v[116:117]
	v_pk_mul_f32 v[50:51], v[50:51], v[152:153]
	v_pk_mul_f32 v[48:49], v[48:49], v[150:151]
	v_pk_mul_f32 v[28:29], v[28:29], v[72:73]
	v_pk_mul_f32 v[24:25], v[24:25], v[76:77]
	v_pk_mul_f32 v[20:21], v[20:21], v[114:115]
	v_pk_mul_f32 v[30:31], v[30:31], v[74:75]
	v_pk_mul_f32 v[26:27], v[26:27], v[78:79]
	v_pk_mul_f32 v[22:23], v[22:23], v[116:117]
	v_pk_mul_f32 v[18:19], v[18:19], v[152:153]
	v_pk_mul_f32 v[16:17], v[16:17], v[150:151]
	v_pk_mul_f32 v[44:45], v[44:45], v[72:73]
	v_pk_mul_f32 v[40:41], v[40:41], v[76:77]
	v_pk_mul_f32 v[36:37], v[36:37], v[114:115]
	v_pk_mul_f32 v[46:47], v[46:47], v[74:75]
	v_pk_mul_f32 v[42:43], v[42:43], v[78:79]
	v_pk_mul_f32 v[38:39], v[38:39], v[116:117]
	v_pk_mul_f32 v[34:35], v[34:35], v[152:153]
	v_pk_mul_f32 v[32:33], v[32:33], v[150:151]
; DEVINL int crow(int r, int hi) { return (r & 3) + 8 * (r >> 2) + 4 * hi; }
; #define SBAR() __builtin_amdgcn_sched_barrier(0)
; #define PVM(db) do { const i32x8 b = {(int)f.v[db][0][0], (int)f.v[db][0][1], (int)f.v[db][0][2], (int)f.v[db][0][3], (int)f.v[db][1][0], (int)f.v[db][1][1], (int)f.v[db][1][2], (int)f.v[db][1][3]}; \
;     o[db] = MFMA8(pa, b, o[db]); } while (0)
; #define TILE_SYNC() do { asm volatile("s_waitcnt vmcnt(0)" ::: "memory"); __syncthreads(); } while (0)
; #define RESC(a) do { if (__any((a) < 1.f)) { if (hi == 0) al_l[r32] = (a); asm volatile("s_waitcnt lgkmcnt(0)" ::: "memory"); \
;     for (int d = 0; d < 4; ++d) for (int r = 0; r < 16; ++r) o[d][r] *= al_l[crow(r, hi)]; } } while (0)
; #define LUPD(al) do { l_reg = l_reg * (al) + lsum[0]; } while (0)
; DEVINL void pv_psm(f32x16* o, const VFrag& f, const i32x8& pa, f32x16& lsum, const i32x8& ones8,
;                    f32x16& p0, f32x16& p1, float& m_reg, float& mn, float& alpha, int kvalid, int hi) {
;     ...
;   if (kvalid < 64) {
; #pragma unroll
;     for (int r = 0; r < 16; ++r) { if (crow(r, hi) >= kvalid) p0[r] = -1e30f; if (32 + crow(r, hi) >= kvalid) p1[r] = -1e30f; }
;   }
;   PVM(0);
;   float pmax = p0[0];
; #pragma unroll
;   for (int r = 1; r < 16; ++r) pmax = fmaxf(pmax, p0[r]);
;   SBAR();
;   PVM(1);
; #pragma unroll
;   for (int r = 0; r < 16; ++r) pmax = fmaxf(pmax, p1[r]);
;   { auto rr = __builtin_amdgcn_permlane32_swap(__float_as_uint(pmax), __float_as_uint(pmax), false, false);
;     pmax = fmaxf(__uint_as_float(rr[0]), __uint_as_float(rr[1])); }
;   SBAR();
;   PVM(2);
;   if (__builtin_expect(__all(pmax - m_reg <= THR / MLA_SCALE), 1)) { mn = m_reg; alpha = 1.f; }
;   else { mn = fmaxf(m_reg, pmax); alpha = __builtin_amdgcn_exp2f((m_reg - mn) * C); m_reg = mn; }
; DEVINL void mla_block(const Params& p, const bf16_t* __restrict__ Qn, const bf16_t* __restrict__ Qr, const char* __restrict__ K8, const char* __restrict__ Kp8,
;                       const char* __restrict__ V8, const bf16_t* __restrict__ Gb, bf16_t* __restrict__ Yb, char* lds, int pos0) {
;     ...
;     qkt<true>(pA0, pA1, KS(j + 1), q8, r32, hi, pB1);
;     pv_load(vf, VS(j), r32, hi); SBAR();
;     finishSM<true>(pB0, pB1, alB, l_reg, pa); SBAR();
;     { const float alPrev = alB; pv_psm(o, vf, pa, lsum, ones8, pA0, pA1, m_reg, mnA, alA, L - (j + 1) * KVBLK, hi); LUPD(alPrev); }
;     TILE_SYNC(); RESC(alA);
.LBB0_572:
	v_pk_fma_f32 v[76:77], v[104:105], s[50:51], v[230:231] op_sel_hi:[1,0,0]
	v_pk_fma_f32 v[68:69], v[96:97], s[50:51], v[230:231] op_sel_hi:[1,0,0]
	v_exp_f32_e32 v198, v77
	v_pk_fma_f32 v[70:71], v[98:99], s[50:51], v[230:231] op_sel_hi:[1,0,0]
	v_pk_fma_f32 v[72:73], v[100:101], s[50:51], v[230:231] op_sel_hi:[1,0,0]
	v_pk_fma_f32 v[74:75], v[102:103], s[50:51], v[230:231] op_sel_hi:[1,0,0]
	v_pk_fma_f32 v[78:79], v[106:107], s[50:51], v[230:231] op_sel_hi:[1,0,0]
	v_pk_fma_f32 v[96:97], v[108:109], s[50:51], v[230:231] op_sel_hi:[1,0,0]
	v_pk_fma_f32 v[98:99], v[110:111], s[50:51], v[230:231] op_sel_hi:[1,0,0]
	v_pk_fma_f32 v[102:103], v[80:81], s[50:51], v[230:231] op_sel_hi:[1,0,0]
	v_pk_fma_f32 v[114:115], v[82:83], s[50:51], v[230:231] op_sel_hi:[1,0,0]
	v_pk_fma_f32 v[116:117], v[84:85], s[50:51], v[230:231] op_sel_hi:[1,0,0]
	v_pk_fma_f32 v[228:229], v[86:87], s[50:51], v[230:231] op_sel_hi:[1,0,0]
	v_pk_fma_f32 v[156:157], v[88:89], s[50:51], v[230:231] op_sel_hi:[1,0,0]
	v_exp_f32_e32 v113, v68
	v_exp_f32_e32 v181, v69
	v_exp_f32_e32 v183, v70
	v_exp_f32_e32 v192, v71
	v_exp_f32_e32 v193, v72
	v_exp_f32_e32 v194, v73
	v_exp_f32_e32 v195, v74
	v_exp_f32_e32 v196, v75
	v_exp_f32_e32 v197, v76
	v_exp_f32_e32 v199, v78
	v_exp_f32_e32 v216, v79
	v_exp_f32_e32 v217, v96
	v_exp_f32_e32 v218, v97
	v_exp_f32_e32 v219, v98
	v_exp_f32_e32 v220, v99
	v_pk_fma_f32 v[158:159], v[90:91], s[50:51], v[230:231] op_sel_hi:[1,0,0]
	v_pk_fma_f32 v[160:161], v[92:93], s[50:51], v[230:231] op_sel_hi:[1,0,0]
	v_pk_fma_f32 v[184:185], v[94:95], s[50:51], v[230:231] op_sel_hi:[1,0,0]
	ds_read_b128 v[98:101], v173 offset:20480
	ds_read_b128 v[104:107], v173 offset:20992
	v_exp_f32_e32 v221, v102
	v_exp_f32_e32 v222, v103
	ds_read_b64 v[102:103], v176 offset:19456
	ds_read_b64 v[108:109], v176 offset:19712
	s_waitcnt lgkmcnt(4)
	v_mfma_scale_f32_32x32x64_f8f6f4 v[66:81], v[200:205], v[120:125], 0, v162, v162 op_sel_hi:[0,0,0] cbsz:2 blgp:2
	v_exp_f32_e32 v223, v114
	v_exp_f32_e32 v224, v115
	v_exp_f32_e32 v225, v116
	v_exp_f32_e32 v226, v117
	v_mfma_scale_f32_32x32x64_f8f6f4 v[82:97], v[206:211], v[120:125], 0, v162, v162 op_sel_hi:[0,0,0] cbsz:2 blgp:2
	ds_read_b128 v[114:117], v173 offset:24576
	ds_read_b128 v[148:151], v173 offset:25088
	ds_read_b64 v[118:119], v176 offset:22528
	ds_read_b64 v[152:153], v176 offset:22784
	s_waitcnt lgkmcnt(4)
	v_mfma_scale_f32_32x32x64_f8f6f4 v[66:81], v[98:103], v[126:131], v[66:81], v162, v162 op_sel_hi:[0,0,0] cbsz:2 blgp:2
	v_exp_f32_e32 v100, v228
	v_exp_f32_e32 v101, v229
	v_exp_f32_e32 v110, v156
	v_exp_f32_e32 v111, v157
	v_exp_f32_e32 v156, v158
	v_exp_f32_e32 v157, v159
	v_mfma_scale_f32_32x32x64_f8f6f4 v[82:97], v[104:109], v[126:131], v[82:97], v162, v162 op_sel_hi:[0,0,0] cbsz:2 blgp:2
	s_waitcnt lgkmcnt(0)
	v_exp_f32_e32 v106, v160
	v_mfma_scale_f32_32x32x64_f8f6f4 v[66:81], v[114:119], v[132:137], v[66:81], v162, v162 op_sel_hi:[0,0,0] cbsz:2 blgp:2
	v_exp_f32_e32 v107, v161
	v_exp_f32_e32 v108, v184
	v_exp_f32_e32 v109, v185
	v_mfma_scale_f32_32x32x64_f8f6f4 v[82:97], v[148:153], v[132:137], v[82:97], v162, v162 op_sel_hi:[0,0,0] cbsz:2 blgp:2
	ds_read_b128 v[148:151], v140 offset:12288
	ds_read_b128 v[152:155], v140 offset:12800
	ds_read_b128 v[184:187], v140 offset:14336
	ds_read_b128 v[188:191], v140 offset:14848
	ds_read_b128 v[200:203], v140 offset:16384
	ds_read_b128 v[204:207], v140 offset:16896
	ds_read_b128 v[208:211], v140 offset:18432
	ds_read_b128 v[212:215], v140 offset:18944
	v_cvt_pk_fp8_f32 v103, v225, v226
	v_cvt_pk_fp8_f32 v98, v113, v181
	v_cvt_pk_fp8_f32 v102, v221, v222
	v_cvt_pk_fp8_f32 v99, v193, v194
	v_cvt_pk_fp8_f32 v103, v100, v101 op_sel:[0,0,1]
	v_cvt_pk_fp8_f32 v100, v197, v198
	v_cvt_pk_fp8_f32 v104, v110, v111
	v_cvt_pk_fp8_f32 v101, v217, v218
	v_cvt_pk_fp8_f32 v105, v106, v107
	v_cvt_pk_fp8_f32 v98, v183, v192 op_sel:[0,0,1]
	v_cvt_pk_fp8_f32 v102, v223, v224 op_sel:[0,0,1]
	v_cvt_pk_fp8_f32 v99, v195, v196 op_sel:[0,0,1]
	v_cvt_pk_fp8_f32 v100, v199, v216 op_sel:[0,0,1]
	v_cvt_pk_fp8_f32 v104, v156, v157 op_sel:[0,0,1]
	v_cvt_pk_fp8_f32 v101, v219, v220 op_sel:[0,0,1]
	v_cvt_pk_fp8_f32 v105, v108, v109 op_sel:[0,0,1]
	s_waitcnt lgkmcnt(0)
	s_nop 0
	v_mfma_scale_f32_32x32x64_f8f6f4 v[0:15], v[98:105], v[148:155], v[0:15], v162, v162 op_sel_hi:[0,0,0]
	v_max_f32_e32 v241, v66, v67
	v_max3_f32 v241, v241, v68, v69
	v_max3_f32 v241, v241, v70, v71
	v_max3_f32 v241, v241, v72, v73
	v_max3_f32 v241, v241, v74, v75
	v_max3_f32 v241, v241, v76, v77
	v_max3_f32 v241, v241, v78, v79
	v_max3_f32 v241, v241, v80, v81
	v_mfma_scale_f32_32x32x64_f8f6f4 v[48:63], v[98:105], v[184:191], v[48:63], v162, v162 op_sel_hi:[0,0,0]
	v_max3_f32 v241, v241, v82, v83
	v_max3_f32 v241, v241, v84, v85
	v_max3_f32 v241, v241, v86, v87
	v_max3_f32 v241, v241, v88, v89
	v_max3_f32 v241, v241, v90, v91
	v_max3_f32 v241, v241, v92, v93
	v_max3_f32 v241, v241, v94, v95
	v_max3_f32 v241, v241, v96, v97
	v_mov_b32_e32 v242, v241
	s_nop 1
	v_permlane32_swap_b32_e32 v241, v242
	v_max_f32_e32 v241, v241, v242
	v_mfma_scale_f32_32x32x64_f8f6f4 v[16:31], v[98:105], v[200:207], v[16:31], v162, v162 op_sel_hi:[0,0,0]
	v_sub_f32_e32 v242, v241, v227
	v_cmp_ge_f32_e32 vcc, s69, v242
	s_cmp_eq_u64 vcc, exec
	s_cselect_b64 s[8:9], -1, 0
	v_mov_b32_e32 v198, 1.0
	v_mfma_scale_f32_32x32x64_f8f6f4 v[32:47], v[98:105], v[208:215], v[32:47], v162, v162 op_sel_hi:[0,0,0]
	s_waitcnt vmcnt(0)
	s_waitcnt vmcnt(0)
	s_barrier
; #define SBAR() __builtin_amdgcn_sched_barrier(0)
; #define RESC(a) do { if (__any((a) < 1.f)) { if (hi == 0) al_l[r32] = (a); asm volatile("s_waitcnt lgkmcnt(0)" ::: "memory"); \
;     for (int d = 0; d < 4; ++d) for (int r = 0; r < 16; ++r) o[d][r] *= al_l[crow(r, hi)]; } } while (0)
; #define LUPD(al) do { l_reg = l_reg * (al) + lsum[0]; } while (0)
; DEVINL void mla_block(const Params& p, const bf16_t* __restrict__ Qn, const bf16_t* __restrict__ Qr, const char* __restrict__ K8, const char* __restrict__ Kp8,
;                       const char* __restrict__ V8, const bf16_t* __restrict__ Gb, bf16_t* __restrict__ Yb, char* lds, int pos0) {
;     ...
;     finishSM<true>(pA0, pA1, alA, l_reg, pa); SBAR();
;     pv_psm(o, vf, pa, lsum, ones8, pB0, pB1, m_reg, mnB, alB, 64, hi);
;     LUPD(alA); RESC(alB); SBAR();
;     qkt<true>(pA0, pA1, KS(j + 1), q8, r32, hi, pB1);
;     pv_load(vf, VS(j), r32, hi); SBAR();
;     finishSM<true>(pB0, pB1, alB, l_reg, pa); SBAR();
;     { const float alPrev = alB; pv_psm(o, vf, pa, lsum, ones8, pA0, pA1, m_reg, mnA, alA, L - (j + 1) * KVBLK, hi); LUPD(alPrev); }
	s_and_b64 vcc, exec, s[8:9]
	s_cbranch_vccnz .LBB0_576
	v_max_f32_e32 v241, v227, v241
	v_sub_f32_e32 v243, v227, v241
	v_mul_f32_e32 v243, 0x3dd53b94, v243
	v_exp_f32_e32 v198, v243
	v_mov_b32_e32 v227, v241
	v_fmamk_f32 v230, v241, 0xbdd53b94, v164
	s_and_saveexec_b64 s[16:17], s[6:7]
	ds_write_b32 v178, v198 offset:128
	s_or_b64 exec, exec, s[16:17]
	s_waitcnt lgkmcnt(0)
	v_add_u32_e32 v242, v171, v177
	ds_read_b128 v[244:247], v242 offset:224
	ds_read_b128 v[116:119], v242 offset:192
	ds_read_b128 v[148:151], v242 offset:160
	ds_read_b128 v[152:155], v242 offset:128
	s_waitcnt lgkmcnt(3)
	v_pk_mul_f32 v[12:13], v[12:13], v[244:245]
	s_waitcnt lgkmcnt(2)
	v_pk_mul_f32 v[8:9], v[8:9], v[116:117]
	s_waitcnt lgkmcnt(1)
	v_pk_mul_f32 v[4:5], v[4:5], v[148:149]
	v_pk_mul_f32 v[14:15], v[14:15], v[246:247]
	v_pk_mul_f32 v[10:11], v[10:11], v[118:119]
	v_pk_mul_f32 v[6:7], v[6:7], v[150:151]
	s_waitcnt lgkmcnt(0)
	v_pk_mul_f32 v[2:3], v[2:3], v[154:155]
	v_pk_mul_f32 v[0:1], v[0:1], v[152:153]
	v_pk_mul_f32 v[60:61], v[60:61], v[244:245]
	v_pk_mul_f32 v[56:57], v[56:57], v[116:117]
	v_pk_mul_f32 v[52:53], v[52:53], v[148:149]
	v_pk_mul_f32 v[62:63], v[62:63], v[246:247]
	v_pk_mul_f32 v[58:59], v[58:59], v[118:119]
	v_pk_mul_f32 v[54:55], v[54:55], v[150:151]
	v_pk_mul_f32 v[50:51], v[50:51], v[154:155]
	v_pk_mul_f32 v[48:49], v[48:49], v[152:153]
	v_pk_mul_f32 v[28:29], v[28:29], v[244:245]
	v_pk_mul_f32 v[24:25], v[24:25], v[116:117]
	v_pk_mul_f32 v[20:21], v[20:21], v[148:149]
	v_pk_mul_f32 v[30:31], v[30:31], v[246:247]
	v_pk_mul_f32 v[26:27], v[26:27], v[118:119]
	v_pk_mul_f32 v[22:23], v[22:23], v[150:151]
	v_pk_mul_f32 v[18:19], v[18:19], v[154:155]
	v_pk_mul_f32 v[16:17], v[16:17], v[152:153]
	v_pk_mul_f32 v[44:45], v[44:45], v[244:245]
	v_pk_mul_f32 v[40:41], v[40:41], v[116:117]
	v_pk_mul_f32 v[36:37], v[36:37], v[148:149]
	v_pk_mul_f32 v[46:47], v[46:47], v[246:247]
	v_pk_mul_f32 v[42:43], v[42:43], v[118:119]
	v_pk_mul_f32 v[38:39], v[38:39], v[150:151]
	v_pk_mul_f32 v[34:35], v[34:35], v[154:155]
	v_pk_mul_f32 v[32:33], v[32:33], v[152:153]
.LBB0_576:
	ds_read_b128 v[204:207], v173 offset:27648
	ds_read_b64 v[208:209], v176 offset:27648
	ds_read_b128 v[216:219], v173 offset:28160
	ds_read_b64 v[220:221], v176 offset:27904
	v_pk_fma_f32 v[228:229], v[74:75], s[50:51], v[230:231] op_sel_hi:[1,0,0]
	v_pk_fma_f32 v[66:67], v[66:67], s[50:51], v[230:231] op_sel_hi:[1,0,0]
	v_pk_fma_f32 v[68:69], v[68:69], s[50:51], v[230:231] op_sel_hi:[1,0,0]
	v_pk_fma_f32 v[70:71], v[70:71], s[50:51], v[230:231] op_sel_hi:[1,0,0]
	v_pk_fma_f32 v[72:73], v[72:73], s[50:51], v[230:231] op_sel_hi:[1,0,0]
	v_pk_fma_f32 v[154:155], v[90:91], s[50:51], v[230:231] op_sel_hi:[1,0,0]
	v_pk_fma_f32 v[152:153], v[92:93], s[50:51], v[230:231] op_sel_hi:[1,0,0]
	v_pk_fma_f32 v[150:151], v[94:95], s[50:51], v[230:231] op_sel_hi:[1,0,0]
	v_pk_fma_f32 v[148:149], v[96:97], s[50:51], v[230:231] op_sel_hi:[1,0,0]
	v_exp_f32_e32 v65, v66
	v_exp_f32_e32 v197, v67
	v_exp_f32_e32 v187, v68
	v_exp_f32_e32 v189, v69
	v_exp_f32_e32 v195, v70
	v_exp_f32_e32 v196, v71
	v_exp_f32_e32 v191, v72
	v_exp_f32_e32 v192, v73
	v_fma_f32 v180, v179, v180, v240
	v_mfma_scale_f32_32x32x64_f8f6f4 v[240:255], v[232:239], v[98:105], 0, v162, v162 op_sel_hi:[0,0,0]
	v_fma_f32 v94, v76, s50, v230
	v_fma_f32 v95, v77, s50, v230
	v_fma_f32 v96, v78, s50, v230
	v_fma_f32 v97, v79, s50, v230
	v_fma_f32 v106, v80, s50, v230
	v_fma_f32 v107, v81, s50, v230
	v_exp_f32_e32 v193, v228
	v_exp_f32_e32 v194, v229
	v_exp_f32_e32 v183, v94
	v_exp_f32_e32 v184, v95
	v_exp_f32_e32 v188, v96
	v_exp_f32_e32 v190, v97
	v_exp_f32_e32 v185, v106
	v_exp_f32_e32 v186, v107
	s_add_i32 s53, s53, 2
	v_pk_fma_f32 v[160:161], v[82:83], s[50:51], v[230:231] op_sel_hi:[1,0,0]
	v_pk_fma_f32 v[158:159], v[84:85], s[50:51], v[230:231] op_sel_hi:[1,0,0]
	v_pk_fma_f32 v[82:83], v[86:87], s[50:51], v[230:231] op_sel_hi:[1,0,0]
	v_pk_fma_f32 v[156:157], v[88:89], s[50:51], v[230:231] op_sel_hi:[1,0,0]
	s_nop 1
	v_fma_f32 v180, v182, v180, v240
	v_mov_b32_e32 v179, v198
.Lu1_560:
	s_cmp_lt_u32 s3, 0x100
	s_cbranch_scc1 .Lu1_dma_done
	s_add_i32 s8, s53, -1
	s_cmpk_lg_i32 s53, 0x102
	s_cselect_b32 s17, s8, 0x100
	s_and_b32 s16, s8, 3
	s_add_i32 s18, s53, -3
	s_cmpk_lt_u32 s18, 0xfe
	s_cselect_b32 s86, s53, 0x100
	s_and_b32 s87, s53, 3
	s_add_i32 s19, s53, -2
	s_and_b32 s20, s19, 3
	s_cmp_lt_u32 s3, 0x180
	s_cbranch_scc1 .Lu1_dma_v
	s_cmp_ge_u32 s3, 0x1c0
	s_cselect_b32 s88, s86, s17
	s_cselect_b32 s89, s87, s16
	s_mul_i32 s89, s89, 0x2400
	s_mul_i32 s92, s88, 0x1800
	s_add_u32 s90, s80, s92
	s_addc_u32 s91, s81, 0
	s_mov_b32 m0, s89
	s_mul_i32 s92, s88, 0xc00
	global_load_lds_dwordx4 v231, s[90:91]
	global_load_lds_dwordx4 v231, s[90:91] offset:1024
	global_load_lds_dwordx4 v231, s[90:91] offset:2048
	global_load_lds_dwordx4 v231, s[90:91] offset:3072
	s_add_u32 s90, s90, 0x1000
	s_addc_u32 s91, s91, 0
	s_add_i32 s88, s89, 0x1000
	s_mov_b32 m0, s88
	s_add_i32 s89, s89, 0x1800
	global_load_lds_dwordx4 v231, s[90:91]
	global_load_lds_dwordx4 v231, s[90:91] offset:1024
	s_add_u32 s90, s82, s92
	s_addc_u32 s91, s83, 0
	s_mov_b32 m0, s89
	s_nop 0
	global_load_lds_dwordx4 v231, s[90:91]
	global_load_lds_dwordx4 v231, s[90:91] offset:1024
	global_load_lds_dwordx4 v231, s[90:91] offset:2048
	s_branch .Lu1_dma_done

; DEVINL int crow(int r, int hi) { return (r & 3) + 8 * (r >> 2) + 4 * hi; }
; #define SBAR() __builtin_amdgcn_sched_barrier(0)
; #define MFMA8(A, B, C) __builtin_amdgcn_mfma_scale_f32_32x32x64_f8f6f4(A, B, C, 0, 0, 0, 0x7f7f7f7f, 0, 0x7f7f7f7f)
; #define PVM(db) do { const i32x8 b = {(int)f.v[db][0][0], (int)f.v[db][0][1], (int)f.v[db][0][2], (int)f.v[db][0][3], (int)f.v[db][1][0], (int)f.v[db][1][1], (int)f.v[db][1][2], (int)f.v[db][1][3]}; \
;     o[db] = MFMA8(pa, b, o[db]); } while (0)
; DEVINL void pv_psm(f32x16* o, const VFrag& f, const i32x8& pa, f32x16& lsum, const i32x8& ones8,
;                    f32x16& p0, f32x16& p1, float& m_reg, float& mn, float& alpha, int kvalid, int hi) {
;   constexpr float C = MLA_SCALE * 1.4426950408889634f;
;     ...
;   if (kvalid < 64) {
; #pragma unroll
;     for (int r = 0; r < 16; ++r) { if (crow(r, hi) >= kvalid) p0[r] = -1e30f; if (32 + crow(r, hi) >= kvalid) p1[r] = -1e30f; }
;   }
;   PVM(0);
;   float pmax = p0[0];
; #pragma unroll
;   for (int r = 1; r < 16; ++r) pmax = fmaxf(pmax, p0[r]);
;   SBAR();
;   PVM(1);
; #pragma unroll
;   for (int r = 0; r < 16; ++r) pmax = fmaxf(pmax, p1[r]);
;   { auto rr = __builtin_amdgcn_permlane32_swap(__float_as_uint(pmax), __float_as_uint(pmax), false, false);
;     pmax = fmaxf(__uint_as_float(rr[0]), __uint_as_float(rr[1])); }
;   SBAR();
;   PVM(2);
;   if (__builtin_expect(__all(pmax - m_reg <= THR / MLA_SCALE), 1)) { mn = m_reg; alpha = 1.f; }
;   else { mn = fmaxf(m_reg, pmax); alpha = __builtin_amdgcn_exp2f((m_reg - mn) * C); m_reg = mn; }
;   const float mnC = PSHIFT - mn * C;
;   const f32x2 C2 = {C, C}, M2 = {mnC, mnC};
; #pragma unroll
;   for (int r = 0; r < 16; r += 2) { f32x2 v = {p0[r], p0[r + 1]}; v = __builtin_elementwise_fma(v, C2, M2); p0[r] = v[0]; p0[r + 1] = v[1]; }
;   SBAR();
;   PVM(3);
; #pragma unroll
;   for (int r = 0; r < 16; r += 2) { f32x2 v = {p1[r], p1[r + 1]}; v = __builtin_elementwise_fma(v, C2, M2); p1[r] = v[0]; p1[r + 1] = v[1]; }
; #pragma unroll
;   for (int r = 0; r < 8; ++r) p0[r] = __builtin_amdgcn_exp2f(p0[r]);
;   SBAR();
;   lsum = MFMA8(ones8, pa, (f32x16{}));
; #pragma unroll
;   for (int r = 8; r < 16; ++r) p0[r] = __builtin_amdgcn_exp2f(p0[r]);
;   SBAR();
;     ...
; }
.Lu1_dma_done:
	ds_read_b128 v[114:117], v173 offset:29696
	ds_read_b128 v[198:201], v173 offset:30208
	ds_read_b64 v[118:119], v176 offset:28672
	ds_read_b64 v[202:203], v176 offset:28928
	v_exp_f32_e32 v182, v82
	s_waitcnt lgkmcnt(4)
	v_exp_f32_e32 v214, v83
	v_mfma_scale_f32_32x32x64_f8f6f4 v[96:111], v[204:209], v[120:125], 0, v162, v162 op_sel_hi:[0,0,0] cbsz:2 blgp:2
	v_exp_f32_e32 v160, v160
	v_exp_f32_e32 v161, v161
	v_exp_f32_e32 v158, v158
	v_exp_f32_e32 v159, v159
	v_mfma_scale_f32_32x32x64_f8f6f4 v[80:95], v[216:221], v[120:125], 0, v162, v162 op_sel_hi:[0,0,0] cbsz:2 blgp:2
	ds_read_b128 v[66:69], v173 offset:33792
	ds_read_b128 v[72:75], v173 offset:34304
	ds_read_b64 v[70:71], v176 offset:31744
	ds_read_b64 v[76:77], v176 offset:32000
	s_waitcnt lgkmcnt(4)
	v_mfma_scale_f32_32x32x64_f8f6f4 v[96:111], v[114:119], v[126:131], v[96:111], v162, v162 op_sel_hi:[0,0,0] cbsz:2 blgp:2
	v_exp_f32_e32 v113, v156
	v_exp_f32_e32 v114, v157
	v_exp_f32_e32 v115, v154
	v_exp_f32_e32 v116, v155
	v_exp_f32_e32 v117, v152
	v_mfma_scale_f32_32x32x64_f8f6f4 v[80:95], v[198:203], v[126:131], v[80:95], v162, v162 op_sel_hi:[0,0,0] cbsz:2 blgp:2
	v_exp_f32_e32 v118, v153
	s_waitcnt lgkmcnt(0)
	v_exp_f32_e32 v119, v150
	v_mfma_scale_f32_32x32x64_f8f6f4 v[96:111], v[66:71], v[132:137], v[96:111], v162, v162 op_sel_hi:[0,0,0] cbsz:2 blgp:2
	v_exp_f32_e32 v156, v151
	v_exp_f32_e32 v157, v148
	v_exp_f32_e32 v215, v149
	v_mfma_scale_f32_32x32x64_f8f6f4 v[80:95], v[72:77], v[132:137], v[80:95], v162, v162 op_sel_hi:[0,0,0] cbsz:2 blgp:2
	ds_read_b128 v[72:75], v140 offset:20480
	ds_read_b128 v[76:79], v140 offset:20992
	ds_read_b128 v[148:151], v140 offset:22528
	ds_read_b128 v[152:155], v140 offset:23040
	ds_read_b128 v[198:201], v140 offset:24576
	ds_read_b128 v[202:205], v140 offset:25088
	ds_read_b128 v[206:209], v140 offset:26624
	ds_read_b128 v[210:213], v140 offset:27136
	v_cvt_pk_fp8_f32 v64, v65, v197
	v_cvt_pk_fp8_f32 v68, v160, v161
	v_cvt_pk_fp8_f32 v65, v195, v196
	v_cvt_pk_fp8_f32 v69, v182, v214
	v_cvt_pk_fp8_f32 v66, v193, v194
	v_cvt_pk_fp8_f32 v70, v115, v116
	v_cvt_pk_fp8_f32 v67, v188, v190
	v_cvt_pk_fp8_f32 v71, v119, v156
	v_cvt_pk_fp8_f32 v64, v187, v189 op_sel:[0,0,1]
	v_cvt_pk_fp8_f32 v68, v158, v159 op_sel:[0,0,1]
	v_cvt_pk_fp8_f32 v65, v191, v192 op_sel:[0,0,1]
	v_cvt_pk_fp8_f32 v69, v113, v114 op_sel:[0,0,1]
	v_cvt_pk_fp8_f32 v66, v183, v184 op_sel:[0,0,1]
	v_cvt_pk_fp8_f32 v70, v117, v118 op_sel:[0,0,1]
	v_cvt_pk_fp8_f32 v67, v185, v186 op_sel:[0,0,1]
	v_cvt_pk_fp8_f32 v71, v157, v215 op_sel:[0,0,1]
	s_waitcnt lgkmcnt(0)
	s_nop 0
	v_mfma_scale_f32_32x32x64_f8f6f4 v[0:15], v[64:71], v[72:79], v[0:15], v162, v162 op_sel_hi:[0,0,0]
	v_max_f32_e32 v113, v96, v97
	v_max3_f32 v113, v113, v98, v99
	v_max3_f32 v113, v113, v100, v101
	v_max3_f32 v113, v113, v102, v103
	v_max3_f32 v113, v113, v104, v105
	v_max3_f32 v113, v113, v106, v107
	v_max3_f32 v113, v113, v108, v109
	v_max3_f32 v113, v113, v110, v111
	v_mfma_scale_f32_32x32x64_f8f6f4 v[48:63], v[64:71], v[148:155], v[48:63], v162, v162 op_sel_hi:[0,0,0]
	v_max3_f32 v72, v113, v80, v81
	v_max3_f32 v72, v72, v82, v83
	v_max3_f32 v72, v72, v84, v85
	v_max3_f32 v72, v72, v86, v87
	v_max3_f32 v72, v72, v88, v89
	v_max3_f32 v72, v72, v90, v91
	v_max3_f32 v72, v72, v92, v93
	v_max3_f32 v72, v72, v94, v95
	v_mov_b32_e32 v73, v72
	s_nop 1
	v_permlane32_swap_b32_e32 v72, v73
	v_max_f32_e32 v72, v72, v73
	v_mfma_scale_f32_32x32x64_f8f6f4 v[16:31], v[64:71], v[198:205], v[16:31], v162, v162 op_sel_hi:[0,0,0]
	v_sub_f32_e32 v73, v72, v227
	v_cmp_ge_f32_e32 vcc, s69, v73
	s_cmp_eq_u64 vcc, exec
	s_cselect_b64 s[8:9], -1, 0
	v_mov_b32_e32 v182, 1.0
	v_mfma_scale_f32_32x32x64_f8f6f4 v[32:47], v[64:71], v[206:213], v[32:47], v162, v162 op_sel_hi:[0,0,0]
	v_mfma_scale_f32_32x32x64_f8f6f4 v[240:255], v[232:239], v[64:71], 0, v162, v162 op_sel_hi:[0,0,0]
	ds_read_b128 v[200:203], v173 offset:0
	ds_read_b64 v[204:205], v176 offset:0
	ds_read_b128 v[206:209], v173 offset:512
	ds_read_b64 v[210:211], v176 offset:256
	s_and_b64 vcc, exec, s[8:9]
	s_cbranch_vccnz .Lu1_572
	v_max_f32_e32 v148, v227, v72
	v_sub_f32_e32 v72, v227, v148
	v_mul_f32_e32 v72, 0x3dd53b94, v72
	v_exp_f32_e32 v182, v72
	v_mov_b32_e32 v227, v148
	v_fmamk_f32 v230, v148, 0xbdd53b94, v164
	s_and_saveexec_b64 s[16:17], s[6:7]
	ds_write_b32 v178, v182 offset:128
	s_or_b64 exec, exec, s[16:17]
	s_waitcnt lgkmcnt(0)
	v_add_u32_e32 v113, v171, v177
	ds_read_b128 v[72:75], v113 offset:224
	ds_read_b128 v[76:79], v113 offset:192
	ds_read_b128 v[114:117], v113 offset:160
	ds_read_b128 v[150:153], v113 offset:128
	s_waitcnt lgkmcnt(0)
	v_pk_mul_f32 v[12:13], v[12:13], v[72:73]
	v_pk_mul_f32 v[8:9], v[8:9], v[76:77]
	v_pk_mul_f32 v[4:5], v[4:5], v[114:115]
	v_pk_mul_f32 v[14:15], v[14:15], v[74:75]
	v_pk_mul_f32 v[10:11], v[10:11], v[78:79]
	v_pk_mul_f32 v[6:7], v[6:7], v[116:117]
	v_pk_mul_f32 v[2:3], v[2:3], v[152:153]
	v_pk_mul_f32 v[0:1], v[0:1], v[150:151]
	v_pk_mul_f32 v[60:61], v[60:61], v[72:73]
	v_pk_mul_f32 v[56:57], v[56:57], v[76:77]
	v_pk_mul_f32 v[52:53], v[52:53], v[114:115]
	v_pk_mul_f32 v[62:63], v[62:63], v[74:75]
	v_pk_mul_f32 v[58:59], v[58:59], v[78:79]
	v_pk_mul_f32 v[54:55], v[54:55], v[116:117]
	v_pk_mul_f32 v[50:51], v[50:51], v[152:153]
	v_pk_mul_f32 v[48:49], v[48:49], v[150:151]
	v_pk_mul_f32 v[28:29], v[28:29], v[72:73]
	v_pk_mul_f32 v[24:25], v[24:25], v[76:77]
	v_pk_mul_f32 v[20:21], v[20:21], v[114:115]
	v_pk_mul_f32 v[30:31], v[30:31], v[74:75]
	v_pk_mul_f32 v[26:27], v[26:27], v[78:79]
	v_pk_mul_f32 v[22:23], v[22:23], v[116:117]
	v_pk_mul_f32 v[18:19], v[18:19], v[152:153]
	v_pk_mul_f32 v[16:17], v[16:17], v[150:151]
	v_pk_mul_f32 v[44:45], v[44:45], v[72:73]
	v_pk_mul_f32 v[40:41], v[40:41], v[76:77]
	v_pk_mul_f32 v[36:37], v[36:37], v[114:115]
	v_pk_mul_f32 v[46:47], v[46:47], v[74:75]
	v_pk_mul_f32 v[42:43], v[42:43], v[78:79]
	v_pk_mul_f32 v[38:39], v[38:39], v[116:117]
	v_pk_mul_f32 v[34:35], v[34:35], v[152:153]
	v_pk_mul_f32 v[32:33], v[32:33], v[150:151]
; #define SBAR() __builtin_amdgcn_sched_barrier(0)
; DEVINL i32x8 mk6(int a, int b, int c, int d, int e, int f) { i32x8 r = __builtin_nondeterministic_value(r); r[0] = a; r[1] = b; r[2] = c; r[3] = d; r[4] = e; r[5] = f; return r; }
; #define MFMA6(A, B, C) __builtin_amdgcn_mfma_scale_f32_32x32x64_f8f6f4(A, B, C, 2, 2, 0, 0x7f7f7f7f, 0, 0x7f7f7f7f)
; template <bool FUSE>
; DEVINL void qkt(f32x16& p0, f32x16& p1, const char* Ks, const i32x8* q8, int r32, int hi, f32x16& e1) {
;   p0 = f32x16{}; p1 = f32x16{};
;   const char* ka = Ks + hi * 1024 + r32 * 16; const char* kb = Ks + 4096 + hi * 512 + r32 * 8;
;   const char* ra = Ks + 6144 + hi * 1024 + r32 * 16; const char* rb = Ks + 6144 + 2048 + hi * 512 + r32 * 8;
;   u32x4 fa[3][2]; u32x2 fb[3][2];
;     ...
;   QK_LD(0, 0);
; #pragma unroll
;   for (int t = 0; t < 3; ++t) {
;     if (t + 1 < 3) QK_LD(t + 1, (t + 1) % 3);
;     const i32x8 a0 = mk6((int)fa[t][0][0], (int)fa[t][0][1], (int)fa[t][0][2], (int)fa[t][0][3], (int)fb[t][0][0], (int)fb[t][0][1]);
;     const i32x8 a1 = mk6((int)fa[t][1][0], (int)fa[t][1][1], (int)fa[t][1][2], (int)fa[t][1][3], (int)fb[t][1][0], (int)fb[t][1][1]);
;     p0 = MFMA6(a0, q8[t], p0);
;     if (FUSE) {
; #pragma unroll
;       for (int r = 0; r < 3; ++r) { const int rr = t * 6 + r; if (rr < 16) e1[rr] = __builtin_amdgcn_exp2f(e1[rr]); }
;     }
;     p1 = MFMA6(a1, q8[t], p1);
;     if (FUSE) {
; #pragma unroll
;       for (int r = 3; r < 6; ++r) { const int rr = t * 6 + r; if (rr < 16) e1[rr] = __builtin_amdgcn_exp2f(e1[rr]); }
;     }
;     SBAR();
;   }
;     ...
; }
; DEVINL void pv_load(VFrag& f, const char* Vs, int r32, int hi) {
;   const char* vb = Vs + hi * 1024 + r32 * 16;
; #pragma unroll
;   for (int db = 0; db < 4; ++db) { f.v[db][0] = *reinterpret_cast<const u32x4*>(vb + db * 2048); f.v[db][1] = *reinterpret_cast<const u32x4*>(vb + db * 2048 + 512); }
; }
.Lu1_572:
	v_pk_fma_f32 v[76:77], v[104:105], s[50:51], v[230:231] op_sel_hi:[1,0,0]
	v_pk_fma_f32 v[68:69], v[96:97], s[50:51], v[230:231] op_sel_hi:[1,0,0]
	v_exp_f32_e32 v198, v77
	v_pk_fma_f32 v[70:71], v[98:99], s[50:51], v[230:231] op_sel_hi:[1,0,0]
	v_pk_fma_f32 v[72:73], v[100:101], s[50:51], v[230:231] op_sel_hi:[1,0,0]
	v_pk_fma_f32 v[74:75], v[102:103], s[50:51], v[230:231] op_sel_hi:[1,0,0]
	v_pk_fma_f32 v[78:79], v[106:107], s[50:51], v[230:231] op_sel_hi:[1,0,0]
	v_pk_fma_f32 v[96:97], v[108:109], s[50:51], v[230:231] op_sel_hi:[1,0,0]
	v_pk_fma_f32 v[98:99], v[110:111], s[50:51], v[230:231] op_sel_hi:[1,0,0]
	v_pk_fma_f32 v[102:103], v[80:81], s[50:51], v[230:231] op_sel_hi:[1,0,0]
	v_pk_fma_f32 v[114:115], v[82:83], s[50:51], v[230:231] op_sel_hi:[1,0,0]
	v_pk_fma_f32 v[116:117], v[84:85], s[50:51], v[230:231] op_sel_hi:[1,0,0]
	v_pk_fma_f32 v[228:229], v[86:87], s[50:51], v[230:231] op_sel_hi:[1,0,0]
	v_pk_fma_f32 v[156:157], v[88:89], s[50:51], v[230:231] op_sel_hi:[1,0,0]
	v_exp_f32_e32 v113, v68
	v_exp_f32_e32 v181, v69
	v_exp_f32_e32 v183, v70
	v_exp_f32_e32 v192, v71
	v_exp_f32_e32 v193, v72
	v_exp_f32_e32 v194, v73
	v_exp_f32_e32 v195, v74
	v_exp_f32_e32 v196, v75
	v_exp_f32_e32 v197, v76
	v_exp_f32_e32 v199, v78
	v_exp_f32_e32 v216, v79
	v_exp_f32_e32 v217, v96
	v_exp_f32_e32 v218, v97
	v_exp_f32_e32 v219, v98
	v_exp_f32_e32 v220, v99
	v_pk_fma_f32 v[158:159], v[90:91], s[50:51], v[230:231] op_sel_hi:[1,0,0]
	v_pk_fma_f32 v[160:161], v[92:93], s[50:51], v[230:231] op_sel_hi:[1,0,0]
	v_pk_fma_f32 v[184:185], v[94:95], s[50:51], v[230:231] op_sel_hi:[1,0,0]
	ds_read_b128 v[98:101], v173 offset:2048
	ds_read_b128 v[104:107], v173 offset:2560
	v_exp_f32_e32 v221, v102
	v_exp_f32_e32 v222, v103
	ds_read_b64 v[102:103], v176 offset:1024
	ds_read_b64 v[108:109], v176 offset:1280
	s_waitcnt lgkmcnt(4)
	v_mfma_scale_f32_32x32x64_f8f6f4 v[66:81], v[200:205], v[120:125], 0, v162, v162 op_sel_hi:[0,0,0] cbsz:2 blgp:2
	v_exp_f32_e32 v223, v114
	v_exp_f32_e32 v224, v115
	v_exp_f32_e32 v225, v116
	v_exp_f32_e32 v226, v117
	v_mfma_scale_f32_32x32x64_f8f6f4 v[82:97], v[206:211], v[120:125], 0, v162, v162 op_sel_hi:[0,0,0] cbsz:2 blgp:2
	ds_read_b128 v[114:117], v173 offset:6144
	ds_read_b128 v[148:151], v173 offset:6656
	ds_read_b64 v[118:119], v176 offset:4096
	ds_read_b64 v[152:153], v176 offset:4352
	s_waitcnt lgkmcnt(4)
	v_mfma_scale_f32_32x32x64_f8f6f4 v[66:81], v[98:103], v[126:131], v[66:81], v162, v162 op_sel_hi:[0,0,0] cbsz:2 blgp:2
	v_exp_f32_e32 v100, v228
	v_exp_f32_e32 v101, v229
	v_exp_f32_e32 v110, v156
	v_exp_f32_e32 v111, v157
	v_exp_f32_e32 v156, v158
	v_exp_f32_e32 v157, v159
	v_mfma_scale_f32_32x32x64_f8f6f4 v[82:97], v[104:109], v[126:131], v[82:97], v162, v162 op_sel_hi:[0,0,0] cbsz:2 blgp:2
	s_waitcnt lgkmcnt(0)
	v_exp_f32_e32 v106, v160
	v_mfma_scale_f32_32x32x64_f8f6f4 v[66:81], v[114:119], v[132:137], v[66:81], v162, v162 op_sel_hi:[0,0,0] cbsz:2 blgp:2
	v_exp_f32_e32 v107, v161
	v_exp_f32_e32 v108, v184
	v_exp_f32_e32 v109, v185
	v_mfma_scale_f32_32x32x64_f8f6f4 v[82:97], v[148:153], v[132:137], v[82:97], v162, v162 op_sel_hi:[0,0,0] cbsz:2 blgp:2
	ds_read_b128 v[148:151], v140 offset:28672
	ds_read_b128 v[152:155], v140 offset:29184
	ds_read_b128 v[184:187], v140 offset:30720
	ds_read_b128 v[188:191], v140 offset:31232
	ds_read_b128 v[200:203], v140 offset:32768
	ds_read_b128 v[204:207], v140 offset:33280
	ds_read_b128 v[208:211], v140 offset:34816
	ds_read_b128 v[212:215], v140 offset:35328
	v_cvt_pk_fp8_f32 v103, v225, v226
	v_cvt_pk_fp8_f32 v98, v113, v181
	v_cvt_pk_fp8_f32 v102, v221, v222
	v_cvt_pk_fp8_f32 v99, v193, v194
	v_cvt_pk_fp8_f32 v103, v100, v101 op_sel:[0,0,1]
	v_cvt_pk_fp8_f32 v100, v197, v198
	v_cvt_pk_fp8_f32 v104, v110, v111
	v_cvt_pk_fp8_f32 v101, v217, v218
	v_cvt_pk_fp8_f32 v105, v106, v107
	v_cvt_pk_fp8_f32 v98, v183, v192 op_sel:[0,0,1]
	v_cvt_pk_fp8_f32 v102, v223, v224 op_sel:[0,0,1]
	v_cvt_pk_fp8_f32 v99, v195, v196 op_sel:[0,0,1]
	v_cvt_pk_fp8_f32 v100, v199, v216 op_sel:[0,0,1]
	v_cvt_pk_fp8_f32 v104, v156, v157 op_sel:[0,0,1]
	v_cvt_pk_fp8_f32 v101, v219, v220 op_sel:[0,0,1]
	v_cvt_pk_fp8_f32 v105, v108, v109 op_sel:[0,0,1]
	s_waitcnt lgkmcnt(0)
	s_nop 0
	v_mfma_scale_f32_32x32x64_f8f6f4 v[0:15], v[98:105], v[148:155], v[0:15], v162, v162 op_sel_hi:[0,0,0]
	s_cmpk_gt_u32 s53, 0x101
	s_cbranch_scc1 .Lmask_last

; #define SBAR() __builtin_amdgcn_sched_barrier(0)
; #define MFMA8(A, B, C) __builtin_amdgcn_mfma_scale_f32_32x32x64_f8f6f4(A, B, C, 0, 0, 0, 0x7f7f7f7f, 0, 0x7f7f7f7f)
; #define PVM(db) do { const i32x8 b = {(int)f.v[db][0][0], (int)f.v[db][0][1], (int)f.v[db][0][2], (int)f.v[db][0][3], (int)f.v[db][1][0], (int)f.v[db][1][1], (int)f.v[db][1][2], (int)f.v[db][1][3]}; \
;     o[db] = MFMA8(pa, b, o[db]); } while (0)
; DEVINL void pv_psm(f32x16* o, const VFrag& f, const i32x8& pa, f32x16& lsum, const i32x8& ones8,
;                    f32x16& p0, f32x16& p1, float& m_reg, float& mn, float& alpha, int kvalid, int hi) {
;     ...
;   const float mnC = PSHIFT - mn * C;
;   const f32x2 C2 = {C, C}, M2 = {mnC, mnC};
; #pragma unroll
;   for (int r = 0; r < 16; r += 2) { f32x2 v = {p0[r], p0[r + 1]}; v = __builtin_elementwise_fma(v, C2, M2); p0[r] = v[0]; p0[r + 1] = v[1]; }
;   SBAR();
;   PVM(3);
; #pragma unroll
;   for (int r = 0; r < 16; r += 2) { f32x2 v = {p1[r], p1[r + 1]}; v = __builtin_elementwise_fma(v, C2, M2); p1[r] = v[0]; p1[r + 1] = v[1]; }
; #pragma unroll
;   for (int r = 0; r < 8; ++r) p0[r] = __builtin_amdgcn_exp2f(p0[r]);
;   SBAR();
;   lsum = MFMA8(ones8, pa, (f32x16{}));
; #pragma unroll
;   for (int r = 8; r < 16; ++r) p0[r] = __builtin_amdgcn_exp2f(p0[r]);
;   SBAR();
;     ...
; }
.Lu1_576:
	ds_read_b128 v[204:207], v173 offset:9216
	ds_read_b64 v[208:209], v176 offset:9216
	ds_read_b128 v[216:219], v173 offset:9728
	ds_read_b64 v[220:221], v176 offset:9472
	v_pk_fma_f32 v[228:229], v[74:75], s[50:51], v[230:231] op_sel_hi:[1,0,0]
	v_pk_fma_f32 v[66:67], v[66:67], s[50:51], v[230:231] op_sel_hi:[1,0,0]
	v_pk_fma_f32 v[68:69], v[68:69], s[50:51], v[230:231] op_sel_hi:[1,0,0]
	v_pk_fma_f32 v[70:71], v[70:71], s[50:51], v[230:231] op_sel_hi:[1,0,0]
	v_pk_fma_f32 v[72:73], v[72:73], s[50:51], v[230:231] op_sel_hi:[1,0,0]
	v_pk_fma_f32 v[154:155], v[90:91], s[50:51], v[230:231] op_sel_hi:[1,0,0]
	v_pk_fma_f32 v[152:153], v[92:93], s[50:51], v[230:231] op_sel_hi:[1,0,0]
	v_pk_fma_f32 v[150:151], v[94:95], s[50:51], v[230:231] op_sel_hi:[1,0,0]
	v_pk_fma_f32 v[148:149], v[96:97], s[50:51], v[230:231] op_sel_hi:[1,0,0]
	v_exp_f32_e32 v65, v66
	v_exp_f32_e32 v197, v67
	v_exp_f32_e32 v187, v68
	v_exp_f32_e32 v189, v69
	v_exp_f32_e32 v195, v70
	v_exp_f32_e32 v196, v71
	v_exp_f32_e32 v191, v72
	v_exp_f32_e32 v192, v73
	v_fma_f32 v180, v179, v180, v240
	v_mfma_scale_f32_32x32x64_f8f6f4 v[240:255], v[232:239], v[98:105], 0, v162, v162 op_sel_hi:[0,0,0]
	v_fma_f32 v94, v76, s50, v230
	v_fma_f32 v95, v77, s50, v230
	v_fma_f32 v96, v78, s50, v230
	v_fma_f32 v97, v79, s50, v230
	v_fma_f32 v106, v80, s50, v230
	v_fma_f32 v107, v81, s50, v230
	v_exp_f32_e32 v193, v228
	v_exp_f32_e32 v194, v229
	v_exp_f32_e32 v183, v94
	v_exp_f32_e32 v184, v95
	v_exp_f32_e32 v188, v96
	v_exp_f32_e32 v190, v97
	v_exp_f32_e32 v185, v106
	v_exp_f32_e32 v186, v107
	s_add_i32 s53, s53, 2
	v_pk_fma_f32 v[160:161], v[82:83], s[50:51], v[230:231] op_sel_hi:[1,0,0]
	v_pk_fma_f32 v[158:159], v[84:85], s[50:51], v[230:231] op_sel_hi:[1,0,0]
	v_pk_fma_f32 v[82:83], v[86:87], s[50:51], v[230:231] op_sel_hi:[1,0,0]
	v_pk_fma_f32 v[156:157], v[88:89], s[50:51], v[230:231] op_sel_hi:[1,0,0]
	s_cmpk_gt_u32 s53, 0x102
	s_nop 1
	v_fma_f32 v180, v182, v180, v240
	s_cbranch_scc1 .LBB0_578
	v_mov_b32_e32 v179, v198
	s_branch .LBB0_560
